# G6: in-proj k-step = all fragment reads, barrier, then 16 MFMAs with the next-next k-tile LDS-DMA spread 1 per 2 MFMAs
# speedup vs baseline: 1.0959x; 1.0050x over previous
.Lg1_loop:
	ds_read_b128 v[82:85], v98 offset:0
	ds_read_b128 v[90:93], v99 offset:0
	ds_read_b128 v[86:89], v98 offset:4096
	ds_read_b128 v[94:97], v99 offset:4096
	ds_read_b128 v[106:109], v100 offset:0
	ds_read_b128 v[114:117], v101 offset:0
	ds_read_b128 v[110:113], v100 offset:4096
	ds_read_b128 v[128:131], v101 offset:4096
	ds_read_b128 v[132:135], v102 offset:0
	ds_read_b128 v[140:143], v103 offset:0
	ds_read_b128 v[136:139], v102 offset:4096
	ds_read_b128 v[144:147], v103 offset:4096
	ds_read_b128 v[148:151], v104 offset:0
	ds_read_b128 v[180:183], v105 offset:0
	ds_read_b128 v[152:155], v104 offset:4096
	ds_read_b128 v[184:187], v105 offset:4096
	s_waitcnt lgkmcnt(0)
	s_barrier
	s_mov_b32 m0, s1
	v_mfma_f32_32x32x16_bf16 v[18:33], v[82:85], v[90:93], v[18:33]
	global_load_lds_dwordx4 v[66:67], off
	v_lshl_add_u64 v[66:67], v[66:67], 0, s[34:35]
	v_mfma_f32_32x32x16_bf16 v[50:65], v[82:85], v[94:97], v[50:65]
	s_mov_b32 m0, s8
	v_mfma_f32_32x32x16_bf16 v[2:17], v[86:89], v[90:93], v[2:17]
	global_load_lds_dwordx4 v[68:69], off
	v_lshl_add_u64 v[68:69], v[68:69], 0, s[34:35]
	v_mfma_f32_32x32x16_bf16 v[34:49], v[86:89], v[94:97], v[34:49]
	s_add_i32 m0, s1, 0x400
	v_mfma_f32_32x32x16_bf16 v[18:33], v[106:109], v[114:117], v[18:33]
	global_load_lds_dwordx4 v[70:71], off
	v_lshl_add_u64 v[70:71], v[70:71], 0, s[34:35]
	v_mfma_f32_32x32x16_bf16 v[50:65], v[106:109], v[128:131], v[50:65]
	s_mov_b32 m0, s9
	v_mfma_f32_32x32x16_bf16 v[2:17], v[110:113], v[114:117], v[2:17]
	global_load_lds_dwordx4 v[72:73], off
	v_lshl_add_u64 v[72:73], v[72:73], 0, s[34:35]
	v_mfma_f32_32x32x16_bf16 v[34:49], v[110:113], v[128:131], v[34:49]
	s_add_i32 m0, s1, 0x800
	v_mfma_f32_32x32x16_bf16 v[18:33], v[132:135], v[140:143], v[18:33]
	global_load_lds_dwordx4 v[74:75], off
	v_lshl_add_u64 v[74:75], v[74:75], 0, s[34:35]
	v_mfma_f32_32x32x16_bf16 v[50:65], v[132:135], v[144:147], v[50:65]
	s_mov_b32 m0, s10
	v_mfma_f32_32x32x16_bf16 v[2:17], v[136:139], v[140:143], v[2:17]
	global_load_lds_dwordx4 v[76:77], off
	v_lshl_add_u64 v[76:77], v[76:77], 0, s[34:35]
	v_mfma_f32_32x32x16_bf16 v[34:49], v[136:139], v[144:147], v[34:49]
	s_add_i32 m0, s1, 0xc00
	v_mfma_f32_32x32x16_bf16 v[18:33], v[148:151], v[180:183], v[18:33]
	global_load_lds_dwordx4 v[78:79], off
	v_lshl_add_u64 v[78:79], v[78:79], 0, s[34:35]
	v_mfma_f32_32x32x16_bf16 v[50:65], v[148:151], v[184:187], v[50:65]
	s_mov_b32 m0, s11
	v_mfma_f32_32x32x16_bf16 v[2:17], v[152:155], v[180:183], v[2:17]
	global_load_lds_dwordx4 v[80:81], off
	v_lshl_add_u64 v[80:81], v[80:81], 0, s[34:35]
	v_mfma_f32_32x32x16_bf16 v[34:49], v[152:155], v[184:187], v[34:49]
	s_waitcnt vmcnt(8)
	s_barrier
	ds_read_b128 v[82:85], v98 offset:32768
	ds_read_b128 v[90:93], v99 offset:32768
	ds_read_b128 v[86:89], v98 offset:36864
	ds_read_b128 v[94:97], v99 offset:36864
	ds_read_b128 v[106:109], v100 offset:32768
	ds_read_b128 v[114:117], v101 offset:32768
	ds_read_b128 v[110:113], v100 offset:36864
	ds_read_b128 v[128:131], v101 offset:36864
	ds_read_b128 v[132:135], v102 offset:32768
	ds_read_b128 v[140:143], v103 offset:32768
	ds_read_b128 v[136:139], v102 offset:36864
	ds_read_b128 v[144:147], v103 offset:36864
	ds_read_b128 v[148:151], v104 offset:32768
	ds_read_b128 v[180:183], v105 offset:32768
	ds_read_b128 v[152:155], v104 offset:36864
	ds_read_b128 v[184:187], v105 offset:36864
	s_waitcnt lgkmcnt(0)
	s_barrier
	s_mov_b32 m0, s6
	v_mfma_f32_32x32x16_bf16 v[18:33], v[82:85], v[90:93], v[18:33]
	global_load_lds_dwordx4 v[66:67], off
	v_lshl_add_u64 v[66:67], v[66:67], 0, s[34:35]
	v_mfma_f32_32x32x16_bf16 v[50:65], v[82:85], v[94:97], v[50:65]
	s_mov_b32 m0, s7
	v_mfma_f32_32x32x16_bf16 v[2:17], v[86:89], v[90:93], v[2:17]
	global_load_lds_dwordx4 v[68:69], off
	v_lshl_add_u64 v[68:69], v[68:69], 0, s[34:35]
	v_mfma_f32_32x32x16_bf16 v[34:49], v[86:89], v[94:97], v[34:49]
	s_mov_b32 m0, s13
	v_mfma_f32_32x32x16_bf16 v[18:33], v[106:109], v[114:117], v[18:33]
	global_load_lds_dwordx4 v[70:71], off
	v_lshl_add_u64 v[70:71], v[70:71], 0, s[34:35]
	v_mfma_f32_32x32x16_bf16 v[50:65], v[106:109], v[128:131], v[50:65]
	s_mov_b32 m0, s14
	v_mfma_f32_32x32x16_bf16 v[2:17], v[110:113], v[114:117], v[2:17]
	global_load_lds_dwordx4 v[72:73], off
	v_lshl_add_u64 v[72:73], v[72:73], 0, s[34:35]
	v_mfma_f32_32x32x16_bf16 v[34:49], v[110:113], v[128:131], v[34:49]
	s_mov_b32 m0, s15
	v_mfma_f32_32x32x16_bf16 v[18:33], v[132:135], v[140:143], v[18:33]
	global_load_lds_dwordx4 v[74:75], off
	v_lshl_add_u64 v[74:75], v[74:75], 0, s[34:35]
	v_mfma_f32_32x32x16_bf16 v[50:65], v[132:135], v[144:147], v[50:65]
	s_mov_b32 m0, s16
	v_mfma_f32_32x32x16_bf16 v[2:17], v[136:139], v[140:143], v[2:17]
	global_load_lds_dwordx4 v[76:77], off
	v_lshl_add_u64 v[76:77], v[76:77], 0, s[34:35]
	v_mfma_f32_32x32x16_bf16 v[34:49], v[136:139], v[144:147], v[34:49]
	s_mov_b32 m0, s17
	v_mfma_f32_32x32x16_bf16 v[18:33], v[148:151], v[180:183], v[18:33]
	global_load_lds_dwordx4 v[78:79], off
	v_lshl_add_u64 v[78:79], v[78:79], 0, s[34:35]
	v_mfma_f32_32x32x16_bf16 v[50:65], v[148:151], v[184:187], v[50:65]
	s_mov_b32 m0, s25
	v_mfma_f32_32x32x16_bf16 v[2:17], v[152:155], v[180:183], v[2:17]
	global_load_lds_dwordx4 v[80:81], off
	v_lshl_add_u64 v[80:81], v[80:81], 0, s[34:35]
	v_mfma_f32_32x32x16_bf16 v[34:49], v[152:155], v[184:187], v[34:49]
	s_waitcnt vmcnt(8)
	s_barrier
	s_add_i32 s12, s12, 2
	s_cmp_lt_u32 s12, 14
	s_cbranch_scc1 .Lg1_loop
	ds_read_b128 v[82:85], v98 offset:0
	ds_read_b128 v[90:93], v99 offset:0
	ds_read_b128 v[86:89], v98 offset:4096
	ds_read_b128 v[94:97], v99 offset:4096
	ds_read_b128 v[106:109], v100 offset:0
	ds_read_b128 v[114:117], v101 offset:0
	ds_read_b128 v[110:113], v100 offset:4096
	ds_read_b128 v[128:131], v101 offset:4096
	ds_read_b128 v[132:135], v102 offset:0
	ds_read_b128 v[140:143], v103 offset:0
	ds_read_b128 v[136:139], v102 offset:4096
	ds_read_b128 v[144:147], v103 offset:4096
	ds_read_b128 v[148:151], v104 offset:0
	ds_read_b128 v[180:183], v105 offset:0
	ds_read_b128 v[152:155], v104 offset:4096
	ds_read_b128 v[184:187], v105 offset:4096
	s_waitcnt lgkmcnt(0)
	s_barrier
	v_mfma_f32_32x32x16_bf16 v[18:33], v[82:85], v[90:93], v[18:33]
	v_mfma_f32_32x32x16_bf16 v[50:65], v[82:85], v[94:97], v[50:65]
	v_mfma_f32_32x32x16_bf16 v[2:17], v[86:89], v[90:93], v[2:17]
	v_mfma_f32_32x32x16_bf16 v[34:49], v[86:89], v[94:97], v[34:49]
	v_mfma_f32_32x32x16_bf16 v[18:33], v[106:109], v[114:117], v[18:33]
	v_mfma_f32_32x32x16_bf16 v[50:65], v[106:109], v[128:131], v[50:65]
	v_mfma_f32_32x32x16_bf16 v[2:17], v[110:113], v[114:117], v[2:17]
	v_mfma_f32_32x32x16_bf16 v[34:49], v[110:113], v[128:131], v[34:49]
	v_mfma_f32_32x32x16_bf16 v[18:33], v[132:135], v[140:143], v[18:33]
	v_mfma_f32_32x32x16_bf16 v[50:65], v[132:135], v[144:147], v[50:65]
	v_mfma_f32_32x32x16_bf16 v[2:17], v[136:139], v[140:143], v[2:17]
	v_mfma_f32_32x32x16_bf16 v[34:49], v[136:139], v[144:147], v[34:49]
	v_mfma_f32_32x32x16_bf16 v[18:33], v[148:151], v[180:183], v[18:33]
	v_mfma_f32_32x32x16_bf16 v[50:65], v[148:151], v[184:187], v[50:65]
	v_mfma_f32_32x32x16_bf16 v[2:17], v[152:155], v[180:183], v[2:17]
	v_mfma_f32_32x32x16_bf16 v[34:49], v[152:155], v[184:187], v[34:49]
	s_waitcnt vmcnt(0)
	s_barrier
	ds_read_b128 v[82:85], v98 offset:32768
	ds_read_b128 v[90:93], v99 offset:32768
	ds_read_b128 v[86:89], v98 offset:36864
	ds_read_b128 v[94:97], v99 offset:36864
	ds_read_b128 v[106:109], v100 offset:32768
	ds_read_b128 v[114:117], v101 offset:32768
	ds_read_b128 v[110:113], v100 offset:36864
	ds_read_b128 v[128:131], v101 offset:36864
	ds_read_b128 v[132:135], v102 offset:32768
	ds_read_b128 v[140:143], v103 offset:32768
	ds_read_b128 v[136:139], v102 offset:36864
	ds_read_b128 v[144:147], v103 offset:36864
	ds_read_b128 v[148:151], v104 offset:32768
	ds_read_b128 v[180:183], v105 offset:32768
	ds_read_b128 v[152:155], v104 offset:36864
	ds_read_b128 v[184:187], v105 offset:36864
	s_waitcnt lgkmcnt(0)
	s_barrier
	v_mfma_f32_32x32x16_bf16 v[18:33], v[82:85], v[90:93], v[18:33]
	v_mfma_f32_32x32x16_bf16 v[50:65], v[82:85], v[94:97], v[50:65]
	v_mfma_f32_32x32x16_bf16 v[2:17], v[86:89], v[90:93], v[2:17]
	v_mfma_f32_32x32x16_bf16 v[34:49], v[86:89], v[94:97], v[34:49]
	v_mfma_f32_32x32x16_bf16 v[18:33], v[106:109], v[114:117], v[18:33]
	v_mfma_f32_32x32x16_bf16 v[50:65], v[106:109], v[128:131], v[50:65]
	v_mfma_f32_32x32x16_bf16 v[2:17], v[110:113], v[114:117], v[2:17]
	v_mfma_f32_32x32x16_bf16 v[34:49], v[110:113], v[128:131], v[34:49]
	v_mfma_f32_32x32x16_bf16 v[18:33], v[132:135], v[140:143], v[18:33]
	v_mfma_f32_32x32x16_bf16 v[50:65], v[132:135], v[144:147], v[50:65]
	v_mfma_f32_32x32x16_bf16 v[2:17], v[136:139], v[140:143], v[2:17]
	v_mfma_f32_32x32x16_bf16 v[34:49], v[136:139], v[144:147], v[34:49]
	v_mfma_f32_32x32x16_bf16 v[18:33], v[148:151], v[180:183], v[18:33]
	v_mfma_f32_32x32x16_bf16 v[50:65], v[148:151], v[184:187], v[50:65]
	v_mfma_f32_32x32x16_bf16 v[2:17], v[152:155], v[180:183], v[2:17]
	v_mfma_f32_32x32x16_bf16 v[34:49], v[152:155], v[184:187], v[34:49]
	s_waitcnt vmcnt(0) lgkmcnt(0)
	s_barrier
